# v7: + MoBA K/V LDS prefetch one tile ahead, SB ring depth 6, xs0 gain/sc loads hoisted
# baseline (speedup 1.0000x reference)
; DI unsigned cvtpk(float lo, float hi) { f32x2_t v = {lo, hi}; bf16x2_t b = __builtin_convertvector(v, bf16x2_t); return __builtin_bit_cast(unsigned, b); }
; DI void xs0_phase(const float* xs, const float* gain, const float* mod_l, bf16* h, unsigned long long* rowsq, int NGW, const int wave_s) {
;     ...
;     for (int m0 = gw; m0 < MTOK; m0 += 4 * NGW) {
;         f32x4 v[4][4];
; #pragma unroll
;         for (int r = 0; r < 4; ++r) { const int m = m0 + r * NGW; const f32x4* xr = (const f32x4*)(xs + (size_t)((m < MTOK) ? m : m0) * DM) + lane;
; #pragma unroll
;             for (int j = 0; j < 4; ++j) v[r][j] = __builtin_nontemporal_load(xr + 64 * j); }
; #pragma unroll
;         for (int r = 0; r < 4; ++r) { const int m = m0 + r * NGW; if (m >= MTOK) break;
;             const int b = m >> 12; float ss = 0.f;
; #pragma unroll
;             for (int j = 0; j < 4; ++j) ss += (v[r][j].x * v[r][j].x + v[r][j].y * v[r][j].y) + (v[r][j].z * v[r][j].z + v[r][j].w * v[r][j].w);
;             ss = wave_sum(ss, x32);
;             if (lane == 0) rowsq[m] = (unsigned long long)(ss * 4294967296.f);
;             unsigned long long* o8 = (unsigned long long*)(h + (size_t)m * DM) + lane;
; #pragma unroll
;             for (int j = 0; j < 4; ++j) { const int col = 4 * lane + 256 * j;
;                 const f32x4 g = *(const f32x4*)(gain + col), sc = *(const f32x4*)(mod_l + (size_t)b * 6144 + DM + col);
;                 const f32x4 y = v[r][j] * (g * (sc + 1.f));
;                 o8[64 * j] = (unsigned long long)cvtpk(y.x, y.y) | ((unsigned long long)cvtpk(y.z, y.w) << 32); } }
.LBB0_107:
	s_or_b64 exec, exec, s[36:37]
	s_mov_b64 s[4:5], s[0:1]
	s_mov_b64 s[10:11], s[0:1]
	s_mov_b64 s[12:13], s[0:1]
	s_mov_b64 s[16:17], s[0:1]
	s_mov_b64 s[14:15], s[0:1]
	v_readlane_b32 s6, v242, 4
	s_waitcnt lgkmcnt(0)
	s_barrier
	v_mbcnt_lo_u32_b32 v0, -1, 0
	v_mbcnt_hi_u32_b32 v0, -1, v0
	s_cmpk_gt_i32 s6, 0x7fff
	s_cbranch_scc1 .LBB0_122
	s_load_dwordx2 s[18:19], s[14:15], 0x90
	s_load_dwordx2 s[26:27], s[4:5], 0x0
	s_load_dwordx2 s[20:21], s[10:11], 0x20
	s_load_dwordx2 s[8:9], s[12:13], 0x90
	s_load_dwordx2 s[24:25], s[16:17], 0x90
	v_ashrrev_i32_e32 v1, 31, v0
	v_lshlrev_b64 v[68:69], 3, v[0:1]
	s_waitcnt lgkmcnt(0)
	s_add_u32 s10, s18, 0x1a800000
	v_lshlrev_b32_e32 v64, 2, v0
	v_lshlrev_b64 v[2:3], 4, v[0:1]
	v_cmp_eq_u32_e64 s[4:5], 0, v0
	v_lshl_add_u64 v[0:1], s[24:25], 0, v[68:69]
	s_mov_b64 s[12:13], 0x6800000
	s_addc_u32 s11, s19, 0
	v_lshl_add_u64 v[70:71], v[0:1], 0, s[12:13]
	s_lshl_b32 s12, s42, 5
	s_add_i32 s18, s6, s95
	s_ashr_i32 s19, s18, 31
	s_ashr_i32 s13, s12, 31
	s_lshl_b32 s45, s42, 4
	s_lshl_b64 s[14:15], s[18:19], 3
	s_lshl_b64 s[16:17], s[12:13], 3
	s_lshl_b64 s[18:19], s[18:19], 11
	s_add_u32 s18, s24, s18
	v_ashrrev_i32_e32 v65, 31, v64
	s_addc_u32 s19, s25, s19
	s_ashr_i32 s7, s6, 31
	v_lshl_add_u64 v[72:73], v[64:65], 2, s[20:21]
	s_lshl_b64 s[20:21], s[12:13], 11
	s_lshl_b64 s[22:23], s[6:7], 3
	s_lshl_b64 s[28:29], s[6:7], 11
	s_add_u32 s24, s24, s28
	s_addc_u32 s25, s25, s29
	s_lshl_b64 s[28:29], s[6:7], 12
	v_lshl_add_u64 v[66:67], s[26:27], 0, v[2:3]
	s_add_u32 s26, s26, s28
	s_addc_u32 s27, s27, s29
	v_xor_b32_e32 v76, 0x80, v64
	s_mul_i32 s50, s42, 24
	v_lshl_add_u64 v[74:75], s[26:27], 0, v[2:3]
	s_lshl_b64 s[26:27], s[12:13], 12
	v_mov_b32_e32 v77, 0
	s_mov_b64 s[28:29], 0x1000
	s_movk_i32 s7, 0x1000
	s_mov_b32 s13, 0x6800000
	s_mov_b64 s[30:31], s[10:11]
	global_load_dwordx4 v[100:103], v[72:73], off
	global_load_dwordx4 v[104:107], v[72:73], off offset:1024
	global_load_dwordx4 v[108:111], v[72:73], off offset:2048
	global_load_dwordx4 v[112:115], v[72:73], off offset:3072
	s_branch .LBB0_111
.LBB0_109:
	s_or_b64 exec, exec, s[36:37]
	s_ashr_i32 s36, s34, 12
	s_lshl_b64 s[34:35], s[34:35], 11
	s_mul_hi_i32 s37, s36, 0x6000
	s_mulk_i32 s36, 0x6000
	s_add_u32 s36, s8, s36
	s_addc_u32 s37, s9, s37
	v_lshl_add_u64 v[24:25], v[64:65], 2, s[36:37]
	v_add_co_u32_e32 v26, vcc, s7, v24
	s_nop 1
	v_addc_co_u32_e32 v27, vcc, 0, v25, vcc
	s_waitcnt lgkmcnt(0)
	global_load_dwordx4 v[116:119], v[26:27], off offset:1024
	global_load_dwordx4 v[120:123], v[26:27], off offset:2048
	global_load_dwordx4 v[124:127], v[26:27], off offset:3072
	global_load_dwordx4 v[16:19], v[26:27], off
	v_mov_b32_e32 v20, v100
	v_mov_b32_e32 v21, v101
	v_mov_b32_e32 v22, v102
	v_mov_b32_e32 v23, v103
	v_lshl_add_u64 v[26:27], v[70:71], 0, s[34:35]
	v_lshl_add_u64 v[24:25], v[24:25], 0, s[28:29]
	s_waitcnt vmcnt(0)
	v_pk_add_f32 v[18:19], v[18:19], 1.0 op_sel_hi:[1,0]
	v_pk_add_f32 v[16:17], v[16:17], 1.0 op_sel_hi:[1,0]
	v_pk_mul_f32 v[18:19], v[22:23], v[18:19]
	v_pk_mul_f32 v[16:17], v[20:21], v[16:17]
	v_pk_mul_f32 v[14:15], v[14:15], v[18:19]
	v_pk_mul_f32 v[12:13], v[12:13], v[16:17]
	s_nop 0
	v_cvt_pk_bf16_f32 v12, v12, v13
	v_cvt_pk_bf16_f32 v13, v14, v15
	global_store_dwordx2 v[26:27], v[12:13], off
	v_mov_b32_e32 v12, v116
	v_mov_b32_e32 v13, v117
	v_mov_b32_e32 v14, v118
	v_mov_b32_e32 v15, v119
	s_nop 0
	v_mov_b32_e32 v16, v104
	v_mov_b32_e32 v17, v105
	v_mov_b32_e32 v18, v106
	v_mov_b32_e32 v19, v107
	v_pk_add_f32 v[14:15], v[14:15], 1.0 op_sel_hi:[1,0]
	v_pk_add_f32 v[12:13], v[12:13], 1.0 op_sel_hi:[1,0]
	v_pk_mul_f32 v[14:15], v[18:19], v[14:15]
	v_pk_mul_f32 v[12:13], v[16:17], v[12:13]
	v_pk_mul_f32 v[10:11], v[10:11], v[14:15]
	v_pk_mul_f32 v[8:9], v[8:9], v[12:13]
	s_nop 0
	v_cvt_pk_bf16_f32 v8, v8, v9
	v_cvt_pk_bf16_f32 v9, v10, v11
	global_store_dwordx2 v[26:27], v[8:9], off offset:512
	v_mov_b32_e32 v8, v120
	v_mov_b32_e32 v9, v121
	v_mov_b32_e32 v10, v122
	v_mov_b32_e32 v11, v123
	s_nop 0
	v_mov_b32_e32 v12, v108
	v_mov_b32_e32 v13, v109
	v_mov_b32_e32 v14, v110
	v_mov_b32_e32 v15, v111
	v_pk_add_f32 v[10:11], v[10:11], 1.0 op_sel_hi:[1,0]
	v_pk_add_f32 v[8:9], v[8:9], 1.0 op_sel_hi:[1,0]
	v_pk_mul_f32 v[10:11], v[14:15], v[10:11]
	v_pk_mul_f32 v[8:9], v[12:13], v[8:9]
	v_pk_mul_f32 v[6:7], v[6:7], v[10:11]
	v_pk_mul_f32 v[4:5], v[4:5], v[8:9]
	s_nop 0
	v_cvt_pk_bf16_f32 v4, v4, v5
	v_cvt_pk_bf16_f32 v5, v6, v7
	global_store_dwordx2 v[26:27], v[4:5], off offset:1024
	v_mov_b32_e32 v4, v124
	v_mov_b32_e32 v5, v125
	v_mov_b32_e32 v6, v126
	v_mov_b32_e32 v7, v127
	s_nop 0
	v_mov_b32_e32 v8, v112
	v_mov_b32_e32 v9, v113
	v_mov_b32_e32 v10, v114
	v_mov_b32_e32 v11, v115
	v_pk_add_f32 v[6:7], v[6:7], 1.0 op_sel_hi:[1,0]
	v_pk_add_f32 v[4:5], v[4:5], 1.0 op_sel_hi:[1,0]
	v_pk_mul_f32 v[6:7], v[10:11], v[6:7]
	v_pk_mul_f32 v[4:5], v[8:9], v[4:5]
	v_pk_mul_f32 v[2:3], v[2:3], v[6:7]
	v_pk_mul_f32 v[0:1], v[0:1], v[4:5]
	s_nop 0
	v_cvt_pk_bf16_f32 v0, v0, v1
	v_cvt_pk_bf16_f32 v1, v2, v3
	global_store_dwordx2 v[26:27], v[0:1], off offset:1536

; DI unsigned cvtpk(float lo, float hi) { f32x2_t v = {lo, hi}; bf16x2_t b = __builtin_convertvector(v, bf16x2_t); return __builtin_bit_cast(unsigned, b); }
; DI void xs0_phase(const float* xs, const float* gain, const float* mod_l, bf16* h, unsigned long long* rowsq, int NGW, const int wave_s) {
;     ...
;         for (int r = 0; r < 4; ++r) { const int m = m0 + r * NGW; if (m >= MTOK) break;
;             const int b = m >> 12; float ss = 0.f;
; #pragma unroll
;             for (int j = 0; j < 4; ++j) ss += (v[r][j].x * v[r][j].x + v[r][j].y * v[r][j].y) + (v[r][j].z * v[r][j].z + v[r][j].w * v[r][j].w);
;             ss = wave_sum(ss, x32);
;             if (lane == 0) rowsq[m] = (unsigned long long)(ss * 4294967296.f);
;             unsigned long long* o8 = (unsigned long long*)(h + (size_t)m * DM) + lane;
; #pragma unroll
;             for (int j = 0; j < 4; ++j) { const int col = 4 * lane + 256 * j;
;                 const f32x4 g = *(const f32x4*)(gain + col), sc = *(const f32x4*)(mod_l + (size_t)b * 6144 + DM + col);
;                 const f32x4 y = v[r][j] * (g * (sc + 1.f));
;                 o8[64 * j] = (unsigned long long)cvtpk(y.x, y.y) | ((unsigned long long)cvtpk(y.z, y.w) << 32); } }
.LBB0_113:
	s_or_b64 exec, exec, s[48:49]
	s_ashr_i32 s39, s6, 12
	s_mul_hi_i32 s49, s39, 0x6000
	s_mulk_i32 s39, 0x6000
	s_add_u32 s48, s8, s39
	s_addc_u32 s49, s9, s49
	v_lshl_add_u64 v[86:87], v[64:65], 2, s[48:49]
	v_add_co_u32_e32 v78, vcc, s7, v86
	v_lshl_add_u64 v[88:89], s[24:25], 0, v[68:69]
	s_waitcnt lgkmcnt(0)
	v_addc_co_u32_e32 v79, vcc, 0, v87, vcc
	global_load_dwordx4 v[116:119], v[78:79], off offset:1024
	global_load_dwordx4 v[120:123], v[78:79], off offset:2048
	global_load_dwordx4 v[124:127], v[78:79], off offset:3072
	global_load_dwordx4 v[78:81], v[78:79], off
	s_nop 0
	v_mov_b32_e32 v82, v100
	v_mov_b32_e32 v83, v101
	v_mov_b32_e32 v84, v102
	v_mov_b32_e32 v85, v103
	v_add_co_u32_e32 v88, vcc, s13, v88
	v_lshl_add_u64 v[86:87], v[86:87], 0, s[28:29]
	s_nop 0
	v_addc_co_u32_e32 v89, vcc, 0, v89, vcc
	s_andn2_b64 vcc, exec, s[46:47]
	s_waitcnt vmcnt(0)
	v_pk_add_f32 v[80:81], v[80:81], 1.0 op_sel_hi:[1,0]
	v_pk_add_f32 v[78:79], v[78:79], 1.0 op_sel_hi:[1,0]
	v_pk_mul_f32 v[80:81], v[84:85], v[80:81]
	v_pk_mul_f32 v[78:79], v[82:83], v[78:79]
	v_pk_mul_f32 v[62:63], v[62:63], v[80:81]
	v_pk_mul_f32 v[60:61], v[60:61], v[78:79]
	s_nop 0
	v_cvt_pk_bf16_f32 v60, v60, v61
	v_cvt_pk_bf16_f32 v61, v62, v63
	global_store_dwordx2 v[88:89], v[60:61], off
	v_mov_b32_e32 v60, v116
	v_mov_b32_e32 v61, v117
	v_mov_b32_e32 v62, v118
	v_mov_b32_e32 v63, v119
	s_nop 0
	v_mov_b32_e32 v78, v104
	v_mov_b32_e32 v79, v105
	v_mov_b32_e32 v80, v106
	v_mov_b32_e32 v81, v107
	v_pk_add_f32 v[62:63], v[62:63], 1.0 op_sel_hi:[1,0]
	v_pk_add_f32 v[60:61], v[60:61], 1.0 op_sel_hi:[1,0]
	v_pk_mul_f32 v[62:63], v[80:81], v[62:63]
	v_pk_mul_f32 v[60:61], v[78:79], v[60:61]
	v_pk_mul_f32 v[58:59], v[58:59], v[62:63]
	v_pk_mul_f32 v[56:57], v[56:57], v[60:61]
	s_nop 0
	v_cvt_pk_bf16_f32 v56, v56, v57
	v_cvt_pk_bf16_f32 v57, v58, v59
	global_store_dwordx2 v[88:89], v[56:57], off offset:512
	v_mov_b32_e32 v56, v120
	v_mov_b32_e32 v57, v121
	v_mov_b32_e32 v58, v122
	v_mov_b32_e32 v59, v123
	s_nop 0
	v_mov_b32_e32 v60, v108
	v_mov_b32_e32 v61, v109
	v_mov_b32_e32 v62, v110
	v_mov_b32_e32 v63, v111
	v_pk_add_f32 v[58:59], v[58:59], 1.0 op_sel_hi:[1,0]
	v_pk_add_f32 v[56:57], v[56:57], 1.0 op_sel_hi:[1,0]
	v_pk_mul_f32 v[58:59], v[62:63], v[58:59]
	v_pk_mul_f32 v[56:57], v[60:61], v[56:57]
	v_pk_mul_f32 v[54:55], v[54:55], v[58:59]
	v_pk_mul_f32 v[52:53], v[52:53], v[56:57]
	s_nop 0
	v_cvt_pk_bf16_f32 v52, v52, v53
	v_cvt_pk_bf16_f32 v53, v54, v55
	global_store_dwordx2 v[88:89], v[52:53], off offset:1024
	v_mov_b32_e32 v52, v124
	v_mov_b32_e32 v53, v125
	v_mov_b32_e32 v54, v126
	v_mov_b32_e32 v55, v127
	s_nop 0
	v_mov_b32_e32 v56, v112
	v_mov_b32_e32 v57, v113
	v_mov_b32_e32 v58, v114
	v_mov_b32_e32 v59, v115
	v_pk_add_f32 v[54:55], v[54:55], 1.0 op_sel_hi:[1,0]
	v_pk_add_f32 v[52:53], v[52:53], 1.0 op_sel_hi:[1,0]
	v_pk_mul_f32 v[54:55], v[58:59], v[54:55]
	v_pk_mul_f32 v[52:53], v[56:57], v[52:53]
	v_pk_mul_f32 v[50:51], v[50:51], v[54:55]
	v_pk_mul_f32 v[48:49], v[48:49], v[52:53]
	s_nop 0
	v_cvt_pk_bf16_f32 v48, v48, v49
	v_cvt_pk_bf16_f32 v49, v50, v51
	global_store_dwordx2 v[88:89], v[48:49], off offset:1536
	s_cbranch_vccnz .LBB0_110
	v_mul_f32_e32 v48, v45, v45
	v_mul_f32_e32 v49, v47, v47
	v_fmac_f32_e32 v48, v44, v44
	v_fmac_f32_e32 v49, v46, v46
	v_add_f32_e32 v48, v48, v49
	v_mul_f32_e32 v49, v41, v41
	v_mul_f32_e32 v50, v43, v43
	v_fmac_f32_e32 v49, v40, v40
	v_fmac_f32_e32 v50, v42, v42
	v_add_f32_e32 v49, v49, v50
	v_add_f32_e32 v48, v48, v49
	v_mul_f32_e32 v49, v37, v37
	v_mul_f32_e32 v50, v39, v39
	v_fmac_f32_e32 v49, v36, v36
	v_fmac_f32_e32 v50, v38, v38
	v_add_f32_e32 v49, v49, v50
	v_add_f32_e32 v48, v48, v49
	v_mul_f32_e32 v49, v33, v33
	v_mul_f32_e32 v50, v35, v35
	v_fmac_f32_e32 v49, v32, v32
	v_fmac_f32_e32 v50, v34, v34
	v_add_f32_e32 v49, v49, v50
	v_add_f32_e32 v48, v48, v49
	ds_swizzle_b32 v49, v48 offset:swizzle(SWAP,1)
	s_waitcnt lgkmcnt(0)
	v_add_f32_e32 v48, v48, v49
	ds_swizzle_b32 v49, v48 offset:swizzle(SWAP,2)
	s_waitcnt lgkmcnt(0)
	v_add_f32_e32 v48, v48, v49
	ds_swizzle_b32 v49, v48 offset:swizzle(SWAP,4)
	s_waitcnt lgkmcnt(0)
	v_add_f32_e32 v48, v48, v49
	ds_swizzle_b32 v49, v48 offset:swizzle(SWAP,8)
	s_waitcnt lgkmcnt(0)
	v_add_f32_e32 v48, v48, v49
	ds_swizzle_b32 v49, v48 offset:swizzle(SWAP,16)
	s_waitcnt lgkmcnt(0)
	v_add_f32_e32 v48, v48, v49
	ds_bpermute_b32 v49, v76, v48
	s_and_saveexec_b64 s[46:47], s[4:5]
	s_cbranch_execz .LBB0_116
	s_waitcnt lgkmcnt(0)
	v_add_f32_e32 v48, v48, v49
	v_mul_f32_e32 v48, 0x4f800000, v48
	v_trunc_f32_e32 v48, v48
	v_mul_f32_e32 v49, 0x2f800000, v48
	v_floor_f32_e32 v49, v49
	v_fmac_f32_e32 v48, 0xcf800000, v49
	v_cvt_u32_f32_e32 v48, v48
	v_cvt_u32_f32_e32 v49, v49
	s_add_u32 s48, s30, s14
	s_addc_u32 s49, s31, s15
	global_store_dwordx2 v77, v[48:49], s[48:49]
; DI unsigned cvtpk(float lo, float hi) { f32x2_t v = {lo, hi}; bf16x2_t b = __builtin_convertvector(v, bf16x2_t); return __builtin_bit_cast(unsigned, b); }
; DI void xs0_phase(const float* xs, const float* gain, const float* mod_l, bf16* h, unsigned long long* rowsq, int NGW, const int wave_s) {
;     ...
;         for (int r = 0; r < 4; ++r) { const int m = m0 + r * NGW; if (m >= MTOK) break;
;             const int b = m >> 12; float ss = 0.f;
; #pragma unroll
;             for (int j = 0; j < 4; ++j) ss += (v[r][j].x * v[r][j].x + v[r][j].y * v[r][j].y) + (v[r][j].z * v[r][j].z + v[r][j].w * v[r][j].w);
;             ss = wave_sum(ss, x32);
;             if (lane == 0) rowsq[m] = (unsigned long long)(ss * 4294967296.f);
;             unsigned long long* o8 = (unsigned long long*)(h + (size_t)m * DM) + lane;
; #pragma unroll
;             for (int j = 0; j < 4; ++j) { const int col = 4 * lane + 256 * j;
;                 const f32x4 g = *(const f32x4*)(gain + col), sc = *(const f32x4*)(mod_l + (size_t)b * 6144 + DM + col);
;                 const f32x4 y = v[r][j] * (g * (sc + 1.f));
;                 o8[64 * j] = (unsigned long long)cvtpk(y.x, y.y) | ((unsigned long long)cvtpk(y.z, y.w) << 32); } }
.LBB0_116:
	s_or_b64 exec, exec, s[46:47]
	s_ashr_i32 s35, s35, 12
	s_mul_hi_i32 s39, s35, 0x6000
	s_mulk_i32 s35, 0x6000
	s_add_u32 s46, s8, s35
	s_addc_u32 s47, s9, s39
	v_lshl_add_u64 v[56:57], v[64:65], 2, s[46:47]
	v_add_co_u32_e32 v48, vcc, s7, v56
	v_lshl_add_u64 v[58:59], s[18:19], 0, v[68:69]
	s_waitcnt lgkmcnt(0)
	v_addc_co_u32_e32 v49, vcc, 0, v57, vcc
	global_load_dwordx4 v[116:119], v[48:49], off offset:1024
	global_load_dwordx4 v[120:123], v[48:49], off offset:2048
	global_load_dwordx4 v[124:127], v[48:49], off offset:3072
	global_load_dwordx4 v[48:51], v[48:49], off
	s_nop 0
	v_mov_b32_e32 v52, v100
	v_mov_b32_e32 v53, v101
	v_mov_b32_e32 v54, v102
	v_mov_b32_e32 v55, v103
	v_add_co_u32_e32 v58, vcc, s13, v58
	v_lshl_add_u64 v[56:57], v[56:57], 0, s[28:29]
	s_nop 0
	v_addc_co_u32_e32 v59, vcc, 0, v59, vcc
	s_andn2_b64 vcc, exec, s[40:41]
	s_waitcnt vmcnt(0)
	v_pk_add_f32 v[50:51], v[50:51], 1.0 op_sel_hi:[1,0]
	v_pk_add_f32 v[48:49], v[48:49], 1.0 op_sel_hi:[1,0]
	v_pk_mul_f32 v[50:51], v[54:55], v[50:51]
	v_pk_mul_f32 v[48:49], v[52:53], v[48:49]
	v_pk_mul_f32 v[46:47], v[46:47], v[50:51]
	v_pk_mul_f32 v[44:45], v[44:45], v[48:49]
	s_nop 0
	v_cvt_pk_bf16_f32 v44, v44, v45
	v_cvt_pk_bf16_f32 v45, v46, v47
	global_store_dwordx2 v[58:59], v[44:45], off
	v_mov_b32_e32 v44, v116
	v_mov_b32_e32 v45, v117
	v_mov_b32_e32 v46, v118
	v_mov_b32_e32 v47, v119
	s_nop 0
	v_mov_b32_e32 v48, v104
	v_mov_b32_e32 v49, v105
	v_mov_b32_e32 v50, v106
	v_mov_b32_e32 v51, v107
	v_pk_add_f32 v[46:47], v[46:47], 1.0 op_sel_hi:[1,0]
	v_pk_add_f32 v[44:45], v[44:45], 1.0 op_sel_hi:[1,0]
	v_pk_mul_f32 v[46:47], v[50:51], v[46:47]
	v_pk_mul_f32 v[44:45], v[48:49], v[44:45]
	v_pk_mul_f32 v[42:43], v[42:43], v[46:47]
	v_pk_mul_f32 v[40:41], v[40:41], v[44:45]
	s_nop 0
	v_cvt_pk_bf16_f32 v40, v40, v41
	v_cvt_pk_bf16_f32 v41, v42, v43
	global_store_dwordx2 v[58:59], v[40:41], off offset:512
	v_mov_b32_e32 v40, v120
	v_mov_b32_e32 v41, v121
	v_mov_b32_e32 v42, v122
	v_mov_b32_e32 v43, v123
	s_nop 0
	v_mov_b32_e32 v44, v108
	v_mov_b32_e32 v45, v109
	v_mov_b32_e32 v46, v110
	v_mov_b32_e32 v47, v111
	v_pk_add_f32 v[42:43], v[42:43], 1.0 op_sel_hi:[1,0]
	v_pk_add_f32 v[40:41], v[40:41], 1.0 op_sel_hi:[1,0]
	v_pk_mul_f32 v[42:43], v[46:47], v[42:43]
	v_pk_mul_f32 v[40:41], v[44:45], v[40:41]
	v_pk_mul_f32 v[38:39], v[38:39], v[42:43]
	v_pk_mul_f32 v[36:37], v[36:37], v[40:41]
	s_nop 0
	v_cvt_pk_bf16_f32 v36, v36, v37
	v_cvt_pk_bf16_f32 v37, v38, v39
	global_store_dwordx2 v[58:59], v[36:37], off offset:1024
	v_mov_b32_e32 v36, v124
	v_mov_b32_e32 v37, v125
	v_mov_b32_e32 v38, v126
	v_mov_b32_e32 v39, v127
	s_nop 0
	v_mov_b32_e32 v40, v112
	v_mov_b32_e32 v41, v113
	v_mov_b32_e32 v42, v114
	v_mov_b32_e32 v43, v115
	v_pk_add_f32 v[38:39], v[38:39], 1.0 op_sel_hi:[1,0]
	v_pk_add_f32 v[36:37], v[36:37], 1.0 op_sel_hi:[1,0]
	v_pk_mul_f32 v[38:39], v[42:43], v[38:39]
	v_pk_mul_f32 v[36:37], v[40:41], v[36:37]
	v_pk_mul_f32 v[34:35], v[34:35], v[38:39]
	v_pk_mul_f32 v[32:33], v[32:33], v[36:37]
	s_nop 0
	v_cvt_pk_bf16_f32 v32, v32, v33
	v_cvt_pk_bf16_f32 v33, v34, v35
	global_store_dwordx2 v[58:59], v[32:33], off offset:1536
	s_cbranch_vccnz .LBB0_110
	v_mul_f32_e32 v32, v29, v29
	v_mul_f32_e32 v33, v31, v31
	v_fmac_f32_e32 v32, v28, v28
	v_fmac_f32_e32 v33, v30, v30
	v_add_f32_e32 v32, v32, v33
	v_mul_f32_e32 v33, v25, v25
	v_mul_f32_e32 v34, v27, v27
	v_fmac_f32_e32 v33, v24, v24
	v_fmac_f32_e32 v34, v26, v26
	v_add_f32_e32 v33, v33, v34
	v_add_f32_e32 v32, v32, v33
	v_mul_f32_e32 v33, v21, v21
	v_mul_f32_e32 v34, v23, v23
	v_fmac_f32_e32 v33, v20, v20
	v_fmac_f32_e32 v34, v22, v22
	v_add_f32_e32 v33, v33, v34
	v_add_f32_e32 v32, v32, v33
	v_mul_f32_e32 v33, v17, v17
	v_mul_f32_e32 v34, v19, v19
	v_fmac_f32_e32 v33, v16, v16
	v_fmac_f32_e32 v34, v18, v18
	v_add_f32_e32 v33, v33, v34
	v_add_f32_e32 v32, v32, v33
	ds_swizzle_b32 v33, v32 offset:swizzle(SWAP,1)
	s_ashr_i32 s39, s38, 31
	s_waitcnt lgkmcnt(0)
	v_add_f32_e32 v32, v32, v33
	ds_swizzle_b32 v33, v32 offset:swizzle(SWAP,2)
	s_waitcnt lgkmcnt(0)
	v_add_f32_e32 v32, v32, v33
	ds_swizzle_b32 v33, v32 offset:swizzle(SWAP,4)
	s_waitcnt lgkmcnt(0)
	v_add_f32_e32 v32, v32, v33
	ds_swizzle_b32 v33, v32 offset:swizzle(SWAP,8)
	s_waitcnt lgkmcnt(0)
	v_add_f32_e32 v32, v32, v33
	ds_swizzle_b32 v33, v32 offset:swizzle(SWAP,16)
	s_waitcnt lgkmcnt(0)
	v_add_f32_e32 v32, v32, v33
	ds_bpermute_b32 v33, v76, v32
	s_and_saveexec_b64 s[40:41], s[4:5]
	s_cbranch_execz .LBB0_119
	s_waitcnt lgkmcnt(0)
	v_add_f32_e32 v32, v32, v33
	v_mul_f32_e32 v32, 0x4f800000, v32
	v_trunc_f32_e32 v32, v32
	v_mul_f32_e32 v33, 0x2f800000, v32
	v_floor_f32_e32 v33, v33
	v_fmac_f32_e32 v32, 0xcf800000, v33
	v_cvt_u32_f32_e32 v32, v32
	v_cvt_u32_f32_e32 v33, v33
	s_lshl_b64 s[46:47], s[38:39], 3
	s_add_u32 s46, s10, s46
	s_addc_u32 s47, s11, s47
	global_store_dwordx2 v77, v[32:33], s[46:47]
; DI unsigned cvtpk(float lo, float hi) { f32x2_t v = {lo, hi}; bf16x2_t b = __builtin_convertvector(v, bf16x2_t); return __builtin_bit_cast(unsigned, b); }
; DI void xs0_phase(const float* xs, const float* gain, const float* mod_l, bf16* h, unsigned long long* rowsq, int NGW, const int wave_s) {
;     ...
;         for (int r = 0; r < 4; ++r) { const int m = m0 + r * NGW; if (m >= MTOK) break;
;             const int b = m >> 12; float ss = 0.f;
; #pragma unroll
;             for (int j = 0; j < 4; ++j) ss += (v[r][j].x * v[r][j].x + v[r][j].y * v[r][j].y) + (v[r][j].z * v[r][j].z + v[r][j].w * v[r][j].w);
;             ss = wave_sum(ss, x32);
;             if (lane == 0) rowsq[m] = (unsigned long long)(ss * 4294967296.f);
;             unsigned long long* o8 = (unsigned long long*)(h + (size_t)m * DM) + lane;
; #pragma unroll
;             for (int j = 0; j < 4; ++j) { const int col = 4 * lane + 256 * j;
;                 const f32x4 g = *(const f32x4*)(gain + col), sc = *(const f32x4*)(mod_l + (size_t)b * 6144 + DM + col);
;                 const f32x4 y = v[r][j] * (g * (sc + 1.f));
;                 o8[64 * j] = (unsigned long long)cvtpk(y.x, y.y) | ((unsigned long long)cvtpk(y.z, y.w) << 32); } }
.LBB0_119:
	s_or_b64 exec, exec, s[40:41]
	s_ashr_i32 s35, s38, 12
	s_lshl_b64 s[38:39], s[38:39], 11
	s_mul_hi_i32 s41, s35, 0x6000
	s_mulk_i32 s35, 0x6000
	s_add_u32 s40, s8, s35
	s_addc_u32 s41, s9, s41
	v_lshl_add_u64 v[40:41], v[64:65], 2, s[40:41]
	v_add_co_u32_e32 v32, vcc, s7, v40
	v_lshl_add_u64 v[42:43], v[70:71], 0, s[38:39]
	s_waitcnt lgkmcnt(0)
	v_addc_co_u32_e32 v33, vcc, 0, v41, vcc
	global_load_dwordx4 v[116:119], v[32:33], off offset:1024
	global_load_dwordx4 v[120:123], v[32:33], off offset:2048
	global_load_dwordx4 v[124:127], v[32:33], off offset:3072
	global_load_dwordx4 v[32:35], v[32:33], off
	s_nop 0
	v_mov_b32_e32 v36, v100
	v_mov_b32_e32 v37, v101
	v_mov_b32_e32 v38, v102
	v_mov_b32_e32 v39, v103
	v_lshl_add_u64 v[40:41], v[40:41], 0, s[28:29]
	s_andn2_b64 vcc, exec, s[36:37]
	s_waitcnt vmcnt(0)
	v_pk_add_f32 v[34:35], v[34:35], 1.0 op_sel_hi:[1,0]
	v_pk_add_f32 v[32:33], v[32:33], 1.0 op_sel_hi:[1,0]
	v_pk_mul_f32 v[34:35], v[38:39], v[34:35]
	v_pk_mul_f32 v[32:33], v[36:37], v[32:33]
	v_pk_mul_f32 v[30:31], v[30:31], v[34:35]
	v_pk_mul_f32 v[28:29], v[28:29], v[32:33]
	s_nop 0
	v_cvt_pk_bf16_f32 v28, v28, v29
	v_cvt_pk_bf16_f32 v29, v30, v31
	global_store_dwordx2 v[42:43], v[28:29], off
	v_mov_b32_e32 v28, v116
	v_mov_b32_e32 v29, v117
	v_mov_b32_e32 v30, v118
	v_mov_b32_e32 v31, v119
	s_nop 0
	v_mov_b32_e32 v32, v104
	v_mov_b32_e32 v33, v105
	v_mov_b32_e32 v34, v106
	v_mov_b32_e32 v35, v107
	v_pk_add_f32 v[30:31], v[30:31], 1.0 op_sel_hi:[1,0]
	v_pk_add_f32 v[28:29], v[28:29], 1.0 op_sel_hi:[1,0]
	v_pk_mul_f32 v[30:31], v[34:35], v[30:31]
	v_pk_mul_f32 v[28:29], v[32:33], v[28:29]
	v_pk_mul_f32 v[26:27], v[26:27], v[30:31]
	v_pk_mul_f32 v[24:25], v[24:25], v[28:29]
	s_nop 0
	v_cvt_pk_bf16_f32 v24, v24, v25
	v_cvt_pk_bf16_f32 v25, v26, v27
	global_store_dwordx2 v[42:43], v[24:25], off offset:512
	v_mov_b32_e32 v24, v120
	v_mov_b32_e32 v25, v121
	v_mov_b32_e32 v26, v122
	v_mov_b32_e32 v27, v123
	s_nop 0
	v_mov_b32_e32 v28, v108
	v_mov_b32_e32 v29, v109
	v_mov_b32_e32 v30, v110
	v_mov_b32_e32 v31, v111
	v_pk_add_f32 v[26:27], v[26:27], 1.0 op_sel_hi:[1,0]
	v_pk_add_f32 v[24:25], v[24:25], 1.0 op_sel_hi:[1,0]
	v_pk_mul_f32 v[26:27], v[30:31], v[26:27]
	v_pk_mul_f32 v[24:25], v[28:29], v[24:25]
	v_pk_mul_f32 v[22:23], v[22:23], v[26:27]
	v_pk_mul_f32 v[20:21], v[20:21], v[24:25]
	s_nop 0
	v_cvt_pk_bf16_f32 v20, v20, v21
	v_cvt_pk_bf16_f32 v21, v22, v23
	global_store_dwordx2 v[42:43], v[20:21], off offset:1024
	v_mov_b32_e32 v20, v124
	v_mov_b32_e32 v21, v125
	v_mov_b32_e32 v22, v126
	v_mov_b32_e32 v23, v127
	s_nop 0
	v_mov_b32_e32 v24, v112
	v_mov_b32_e32 v25, v113
	v_mov_b32_e32 v26, v114
	v_mov_b32_e32 v27, v115
	v_pk_add_f32 v[22:23], v[22:23], 1.0 op_sel_hi:[1,0]
	v_pk_add_f32 v[20:21], v[20:21], 1.0 op_sel_hi:[1,0]
	v_pk_mul_f32 v[22:23], v[26:27], v[22:23]
	v_pk_mul_f32 v[20:21], v[24:25], v[20:21]
	v_pk_mul_f32 v[18:19], v[18:19], v[22:23]
	v_pk_mul_f32 v[16:17], v[16:17], v[20:21]
	s_nop 0
	v_cvt_pk_bf16_f32 v16, v16, v17
	v_cvt_pk_bf16_f32 v17, v18, v19
	global_store_dwordx2 v[42:43], v[16:17], off offset:1536
	s_cbranch_vccnz .LBB0_110
	v_mul_f32_e32 v16, v13, v13
	v_mul_f32_e32 v17, v15, v15
	v_fmac_f32_e32 v16, v12, v12
	v_fmac_f32_e32 v17, v14, v14
	v_add_f32_e32 v16, v16, v17
	v_mul_f32_e32 v17, v9, v9
	v_mul_f32_e32 v18, v11, v11
	v_fmac_f32_e32 v17, v8, v8
	v_fmac_f32_e32 v18, v10, v10
	v_add_f32_e32 v17, v17, v18
	v_add_f32_e32 v16, v16, v17
	v_mul_f32_e32 v17, v5, v5
	v_mul_f32_e32 v18, v7, v7
	v_fmac_f32_e32 v17, v4, v4
	v_fmac_f32_e32 v18, v6, v6
	v_add_f32_e32 v17, v17, v18
	v_add_f32_e32 v16, v16, v17
	v_mul_f32_e32 v17, v1, v1
	v_mul_f32_e32 v18, v3, v3
	v_fmac_f32_e32 v17, v0, v0
	v_fmac_f32_e32 v18, v2, v2
	v_add_f32_e32 v17, v17, v18
	v_add_f32_e32 v16, v16, v17
	ds_swizzle_b32 v17, v16 offset:swizzle(SWAP,1)
	s_ashr_i32 s35, s34, 31
	s_waitcnt lgkmcnt(0)
	v_add_f32_e32 v16, v16, v17
	ds_swizzle_b32 v17, v16 offset:swizzle(SWAP,2)
	s_waitcnt lgkmcnt(0)
	v_add_f32_e32 v16, v16, v17
	ds_swizzle_b32 v17, v16 offset:swizzle(SWAP,4)
	s_waitcnt lgkmcnt(0)
	v_add_f32_e32 v16, v16, v17
	ds_swizzle_b32 v17, v16 offset:swizzle(SWAP,8)
	s_waitcnt lgkmcnt(0)
	v_add_f32_e32 v16, v16, v17
	ds_swizzle_b32 v17, v16 offset:swizzle(SWAP,16)
	s_waitcnt lgkmcnt(0)
	v_add_f32_e32 v16, v16, v17
	ds_bpermute_b32 v17, v76, v16
	s_and_saveexec_b64 s[36:37], s[4:5]
	s_cbranch_execz .LBB0_109
	s_waitcnt lgkmcnt(0)
	v_add_f32_e32 v16, v16, v17
	v_mul_f32_e32 v16, 0x4f800000, v16
	v_trunc_f32_e32 v16, v16
	v_mul_f32_e32 v17, 0x2f800000, v16
	v_floor_f32_e32 v17, v17
	v_fmac_f32_e32 v16, 0xcf800000, v17
	v_cvt_u32_f32_e32 v16, v16
	v_cvt_u32_f32_e32 v17, v17
	s_lshl_b64 s[38:39], s[34:35], 3
	s_add_u32 s38, s10, s38
	s_addc_u32 s39, s11, s39
	global_store_dwordx2 v77, v[16:17], s[38:39]
	s_branch .LBB0_109

; #define LAS __attribute__((address_space(3)))
; DI void moba_wg_phase(const bf16* qb, const unsigned char* kfb, const unsigned char* vfb, bf16* ob, const bf16* kmean, const float* gains, int G, LAS unsigned char* lds, const int wave_s) {
;     ...
;             if (need) { const int ntile = (n < own) ? 8 : (wave + 1);
;                 for (int t = 0; t < ntile; ++t) {
;                     const LAS unsigned char* sl = lds + (unsigned)(n & 1) * 65536u + (unsigned)t * 8192u + lofs; bf16x8 kf[4], vf[4];
;                     kf[0] = *(const LAS bf16x8*)(sl); kf[1] = *(const LAS bf16x8*)(sl + 1024); kf[2] = *(const LAS bf16x8*)(sl + 2048); kf[3] = *(const LAS bf16x8*)(sl + 3072);
;                     vf[0] = *(const LAS bf16x8*)(sl + 4096); vf[1] = *(const LAS bf16x8*)(sl + 5120); vf[2] = *(const LAS bf16x8*)(sl + 6144); vf[3] = *(const LAS bf16x8*)(sl + 7168);
;                     (void)attn_tile<1>(kf, vf, qf, n * 256 + 32 * t, q0, tq, hi, xq, own, selmask, m_run, l_run, O0, O1); } }
.LBB0_505:
	v_cndmask_b32_e64 v0, 0, 1, s[50:51]
	v_lshl_add_u32 v0, v0, 16, v107
	s_mov_b32 s97, s80
	s_waitcnt lgkmcnt(0)
	ds_read_b128 v[214:217], v0
	ds_read_b128 v[218:221], v0 offset:1024
	ds_read_b128 v[222:225], v0 offset:2048
	ds_read_b128 v[226:229], v0 offset:3072
	ds_read_b128 v[90:93], v0 offset:4096
	ds_read_b128 v[86:89], v0 offset:5120
	ds_read_b128 v[94:97], v0 offset:6144
	ds_read_b128 v[82:85], v0 offset:7168
	s_branch .LBB0_507
.LBB0_506:
	s_nop 8
	v_cvt_pk_bf16_f32 v34, v50, v51
	v_cvt_pk_bf16_f32 v35, v52, v53
	v_cvt_pk_bf16_f32 v36, v54, v55
	v_cvt_pk_bf16_f32 v37, v56, v57
	v_exp_f32_e32 v38, v65
	s_add_i32 s68, s68, -1
	s_waitcnt lgkmcnt(4)
	v_mfma_f32_32x32x16_bf16 v[18:33], v[90:93], v[34:37], v[18:33]
	s_add_i32 s97, s97, 32
	v_add_f32_e32 v108, v38, v109
	v_add_u32_e32 v0, 0x2000, v0
	s_cmp_lg_u32 s68, 0
	v_mfma_f32_32x32x16_bf16 v[2:17], v[94:97], v[34:37], v[2:17]
	v_cvt_pk_bf16_f32 v34, v58, v59
	v_cvt_pk_bf16_f32 v35, v60, v61
	v_cvt_pk_bf16_f32 v36, v62, v63
	v_cvt_pk_bf16_f32 v37, v64, v38
	s_nop 1
	v_mfma_f32_32x32x16_bf16 v[18:33], v[86:89], v[34:37], v[18:33]
	v_mfma_f32_32x32x16_bf16 v[2:17], v[82:85], v[34:37], v[2:17]
	ds_read_b128 v[90:93], v0 offset:4096
	ds_read_b128 v[86:89], v0 offset:5120
	ds_read_b128 v[94:97], v0 offset:6144
	ds_read_b128 v[82:85], v0 offset:7168
	s_cbranch_scc0 .LBB0_515
.LBB0_507:
	s_cmp_lg_u32 s96, s97
	s_mov_b64 s[46:47], -1
	s_waitcnt lgkmcnt(4)
	v_mfma_f32_32x32x16_bf16 v[34:49], v[214:217], v[66:69], 0
	v_mfma_f32_32x32x16_bf16 v[34:49], v[218:221], v[70:73], v[34:49]
	v_mfma_f32_32x32x16_bf16 v[34:49], v[222:225], v[74:77], v[34:49]
	v_mfma_f32_32x32x16_bf16 v[34:49], v[226:229], v[78:81], v[34:49]
	ds_read_b128 v[214:217], v0 offset:8192
	ds_read_b128 v[218:221], v0 offset:9216
	ds_read_b128 v[222:225], v0 offset:10240
	ds_read_b128 v[226:229], v0 offset:11264
	s_cbranch_scc0 .LBB0_513
	s_lshr_b32 s58, s97, 8
	s_cmp_eq_u32 s58, s95
	s_cselect_b64 s[46:47], -1, 0
	s_and_b64 vcc, exec, s[46:47]
	s_cbranch_vccnz .LBB0_510
	v_lshrrev_b32_e32 v50, s58, v103
	v_and_b32_e32 v50, 1, v50
	v_cmp_eq_u32_e32 vcc, 1, v50
	s_andn2_b64 s[46:47], s[46:47], exec
	s_and_b64 s[58:59], vcc, exec
	s_or_b64 s[46:47], s[46:47], s[58:59]

; #define LAS __attribute__((address_space(3)))
; DI void sb_wg_phase(const bf16* qb, const unsigned char* kfb, const unsigned char* vfb, bf16* ob, int G, LAS unsigned char* lds, const int wave_s) {
;     ...
;         int lane_u = lane; asm volatile("" : "+v"(lane_u));
;         const int hi = lane_u >> 5, col = lane_u & 31, xq = (lane_u ^ 32) << 2; const unsigned lofs = (unsigned)lane_u * 16u;
;         const int bh = xx * (128 / nx) + (v >> 4), b = bh >> 4, h = bh & 15, qc0 = (v & 15) * 8, qc = qc0 + wave, q0 = 32 * qc, tq = q0 + col, tok0 = b * SEQ;
;         const size_t hbase = (size_t)((b * 16 + h) * 128) << 12;
;         const char* gsrc = (const char*)((wave < 4) ? kfb : vfb) + hbase + (unsigned)(wave & 3) * 1024u + lofs;
;         const int tlo = (qc0 >= 8) ? qc0 - 8 : 0;
;         for (int t = tlo; t < qc0 + 8; ++t)
;             __builtin_amdgcn_global_load_lds((const unsigned*)(gsrc + (size_t)t * 4096), (LAS unsigned*)(lds + (unsigned)(t & 15) * 8192u + wpiece), 16, 0, 0);
.LBB0_524:
	s_ashr_i32 s4, s94, 4
	v_readlane_b32 s5, v242, 10
	s_add_i32 s5, s4, s5
	s_lshl_b32 s6, s94, 3
	s_lshl_b32 s8, s5, 7
	s_and_b32 s6, s6, 0x78
	s_ashr_i32 s9, s8, 31
	s_lshl_b64 vcc, s[8:9], 12
	s_add_i32 s7, s6, -6
	s_cmp_lg_u32 s6, 0
	s_cselect_b32 s58, s7, 0
	s_ashr_i32 s59, s58, 31
	s_or_b32 s7, s6, 7
	s_add_i32 s8, s58, -1
	s_lshl_b32 s9, s58, 13
	s_lshl_b64 s[10:11], s[58:59], 12
	s_add_u32 s10, s10, vcc_lo
	s_addc_u32 s11, s11, vcc_hi
	v_mov_b32_e32 v4, v120
	s_add_u32 s10, s44, s10
	s_addc_u32 s11, s54, s11
	v_lshlrev_b32_e32 v0, 4, v4
	v_lshl_add_u64 v[2:3], s[10:11], 0, v[0:1]
